# v77 + grid barrier: dropped the per-XCD release atomic nobody polls any more (leader no longer waits for it before its closing barrier)
# speedup vs baseline: 1.0022x; 1.0022x over previous
; __device__ __forceinline__ unsigned xb_ld(unsigned* p)              { return __hip_atomic_load(p, __ATOMIC_RELAXED, __HIP_MEMORY_SCOPE_AGENT); }
; __device__ __forceinline__ unsigned xb_add(unsigned* p, unsigned v) { return __hip_atomic_fetch_add(p, v, __ATOMIC_RELAXED, __HIP_MEMORY_SCOPE_AGENT); }
; #define XB_SPIN(cond, bar) do { unsigned _sp = 0; while (cond) { __builtin_amdgcn_s_sleep(1); \
;     if ((++_sp & 255u) == 0u) { if (xb_ld(&(bar)[XB_TMO])) break; if (_sp > XB_SPIN_CAP) { atomicAdd(&(bar)[XB_TMO], 1u); break; } } } } while (0)
; __device__ __forceinline__ void xcd_barrier(const XcdBarrier& b) {
;     ...
;             if (og + 1u == (tg + 1u) * nx) xb_add(&bar[XB_TOPGEN], 1u);
;             else XB_SPIN(xb_ld(&bar[XB_TOPGEN]) == tg, bar);
;             __builtin_amdgcn_fence(__ATOMIC_ACQUIRE, "agent");
;             xb_add(&bar[XB_XGEN(b.x)], 1u);
;             asm volatile("s_waitcnt vmcnt(0)" ::: "memory");
.LBB0_174:
	s_or_b64 exec, exec, s[14:15]
	s_mov_b64 s[14:15], exec
	v_mbcnt_lo_u32_b32 v0, s14, 0
	v_mbcnt_hi_u32_b32 v0, s15, v0
	v_cmp_eq_u32_e32 vcc, 0, v0
	s_waitcnt vmcnt(0)
	buffer_inv sc1
	s_and_saveexec_b64 s[20:21], vcc
	s_cbranch_execz .LBB0_176
	s_bcnt1_i32_b64 s2, s[14:15]
	v_mov_b32_e32 v0, s2
	v_readlane_b32 s2, v253, 61
	v_readlane_b32 s3, v253, 62
	s_nop 4
.LBB0_176:
	s_or_b64 exec, exec, s[20:21]
	s_waitcnt vmcnt(0)

; __device__ __forceinline__ unsigned xb_ld(unsigned* p)              { return __hip_atomic_load(p, __ATOMIC_RELAXED, __HIP_MEMORY_SCOPE_AGENT); }
; __device__ __forceinline__ unsigned xb_add(unsigned* p, unsigned v) { return __hip_atomic_fetch_add(p, v, __ATOMIC_RELAXED, __HIP_MEMORY_SCOPE_AGENT); }
; #define XB_SPIN(cond, bar) do { unsigned _sp = 0; while (cond) { __builtin_amdgcn_s_sleep(1); \
;     if ((++_sp & 255u) == 0u) { if (xb_ld(&(bar)[XB_TMO])) break; if (_sp > XB_SPIN_CAP) { atomicAdd(&(bar)[XB_TMO], 1u); break; } } } } while (0)
; __device__ __forceinline__ void xcd_barrier(const XcdBarrier& b) {
;     ...
;             if (og + 1u == (tg + 1u) * nx) xb_add(&bar[XB_TOPGEN], 1u);
;             else XB_SPIN(xb_ld(&bar[XB_TOPGEN]) == tg, bar);
;             __builtin_amdgcn_fence(__ATOMIC_ACQUIRE, "agent");
;             xb_add(&bar[XB_XGEN(b.x)], 1u);
;             asm volatile("s_waitcnt vmcnt(0)" ::: "memory");
.LBB0_439:
	s_or_b64 exec, exec, s[10:11]
	s_mov_b64 s[10:11], exec
	v_mbcnt_lo_u32_b32 v0, s10, 0
	v_mbcnt_hi_u32_b32 v0, s11, v0
	v_cmp_eq_u32_e32 vcc, 0, v0
	s_waitcnt vmcnt(0)
	buffer_inv sc1
	s_and_saveexec_b64 s[14:15], vcc
	s_cbranch_execz .LBB0_441
	s_bcnt1_i32_b64 s2, s[10:11]
	v_mov_b32_e32 v0, s2
	v_readlane_b32 s2, v253, 61
	v_readlane_b32 s3, v253, 62
	s_nop 4
.LBB0_441:
	s_or_b64 exec, exec, s[14:15]
	s_waitcnt vmcnt(0)

; __device__ __forceinline__ unsigned xb_ld(unsigned* p)              { return __hip_atomic_load(p, __ATOMIC_RELAXED, __HIP_MEMORY_SCOPE_AGENT); }
; __device__ __forceinline__ unsigned xb_add(unsigned* p, unsigned v) { return __hip_atomic_fetch_add(p, v, __ATOMIC_RELAXED, __HIP_MEMORY_SCOPE_AGENT); }
; #define XB_SPIN(cond, bar) do { unsigned _sp = 0; while (cond) { __builtin_amdgcn_s_sleep(1); \
;     if ((++_sp & 255u) == 0u) { if (xb_ld(&(bar)[XB_TMO])) break; if (_sp > XB_SPIN_CAP) { atomicAdd(&(bar)[XB_TMO], 1u); break; } } } } while (0)
; __device__ __forceinline__ void xcd_barrier(const XcdBarrier& b) {
;     ...
;             if (og + 1u == (tg + 1u) * nx) xb_add(&bar[XB_TOPGEN], 1u);
;             else XB_SPIN(xb_ld(&bar[XB_TOPGEN]) == tg, bar);
;             __builtin_amdgcn_fence(__ATOMIC_ACQUIRE, "agent");
;             xb_add(&bar[XB_XGEN(b.x)], 1u);
;             asm volatile("s_waitcnt vmcnt(0)" ::: "memory");
.LBB0_540:
	s_or_b64 exec, exec, s[10:11]
	s_mov_b64 s[10:11], exec
	v_mbcnt_lo_u32_b32 v0, s10, 0
	v_mbcnt_hi_u32_b32 v0, s11, v0
	v_cmp_eq_u32_e32 vcc, 0, v0
	s_waitcnt vmcnt(0)
	buffer_inv sc1
	s_and_saveexec_b64 s[14:15], vcc
	s_cbranch_execz .LBB0_542
	s_bcnt1_i32_b64 s2, s[10:11]
	v_mov_b32_e32 v0, s2
	v_readlane_b32 s2, v253, 61
	v_readlane_b32 s3, v253, 62
	s_nop 4
.LBB0_542:
	s_or_b64 exec, exec, s[14:15]
	s_waitcnt vmcnt(0)

; __device__ __forceinline__ unsigned xb_ld(unsigned* p)              { return __hip_atomic_load(p, __ATOMIC_RELAXED, __HIP_MEMORY_SCOPE_AGENT); }
; __device__ __forceinline__ unsigned xb_add(unsigned* p, unsigned v) { return __hip_atomic_fetch_add(p, v, __ATOMIC_RELAXED, __HIP_MEMORY_SCOPE_AGENT); }
; #define XB_SPIN(cond, bar) do { unsigned _sp = 0; while (cond) { __builtin_amdgcn_s_sleep(1); \
;     if ((++_sp & 255u) == 0u) { if (xb_ld(&(bar)[XB_TMO])) break; if (_sp > XB_SPIN_CAP) { atomicAdd(&(bar)[XB_TMO], 1u); break; } } } } while (0)
; __device__ __forceinline__ void xcd_barrier(const XcdBarrier& b) {
;     ...
;             if (og + 1u == (tg + 1u) * nx) xb_add(&bar[XB_TOPGEN], 1u);
;             else XB_SPIN(xb_ld(&bar[XB_TOPGEN]) == tg, bar);
;             __builtin_amdgcn_fence(__ATOMIC_ACQUIRE, "agent");
;             xb_add(&bar[XB_XGEN(b.x)], 1u);
;             asm volatile("s_waitcnt vmcnt(0)" ::: "memory");
.LBB0_660:
	s_or_b64 exec, exec, s[8:9]
	s_mov_b64 s[8:9], exec
	v_mbcnt_lo_u32_b32 v0, s8, 0
	v_mbcnt_hi_u32_b32 v0, s9, v0
	v_cmp_eq_u32_e32 vcc, 0, v0
	s_waitcnt vmcnt(0)
	buffer_inv sc1
	s_and_saveexec_b64 s[10:11], vcc
	s_cbranch_execz .LBB0_662
	s_bcnt1_i32_b64 s2, s[8:9]
	v_mov_b32_e32 v0, s2
	v_readlane_b32 s2, v253, 61
	v_readlane_b32 s3, v253, 62
	s_nop 4
.LBB0_662:
	s_or_b64 exec, exec, s[10:11]
	s_waitcnt vmcnt(0)

; __device__ __forceinline__ unsigned xb_ld(unsigned* p)              { return __hip_atomic_load(p, __ATOMIC_RELAXED, __HIP_MEMORY_SCOPE_AGENT); }
; __device__ __forceinline__ unsigned xb_add(unsigned* p, unsigned v) { return __hip_atomic_fetch_add(p, v, __ATOMIC_RELAXED, __HIP_MEMORY_SCOPE_AGENT); }
; #define XB_SPIN(cond, bar) do { unsigned _sp = 0; while (cond) { __builtin_amdgcn_s_sleep(1); \
;     if ((++_sp & 255u) == 0u) { if (xb_ld(&(bar)[XB_TMO])) break; if (_sp > XB_SPIN_CAP) { atomicAdd(&(bar)[XB_TMO], 1u); break; } } } } while (0)
; __device__ __forceinline__ void xcd_barrier(const XcdBarrier& b) {
;     ...
;             if (og + 1u == (tg + 1u) * nx) xb_add(&bar[XB_TOPGEN], 1u);
;             else XB_SPIN(xb_ld(&bar[XB_TOPGEN]) == tg, bar);
;             __builtin_amdgcn_fence(__ATOMIC_ACQUIRE, "agent");
;             xb_add(&bar[XB_XGEN(b.x)], 1u);
;             asm volatile("s_waitcnt vmcnt(0)" ::: "memory");
.LBB0_767:
	s_or_b64 exec, exec, s[8:9]
	s_mov_b64 s[8:9], exec
	v_mbcnt_lo_u32_b32 v0, s8, 0
	v_mbcnt_hi_u32_b32 v0, s9, v0
	v_cmp_eq_u32_e32 vcc, 0, v0
	s_waitcnt vmcnt(0)
	buffer_inv sc1
	s_and_saveexec_b64 s[10:11], vcc
	s_cbranch_execz .LBB0_769
	s_bcnt1_i32_b64 s2, s[8:9]
	v_mov_b32_e32 v0, s2
	v_readlane_b32 s2, v253, 61
	v_readlane_b32 s3, v253, 62
	s_nop 4
.LBB0_769:
	s_or_b64 exec, exec, s[10:11]
	s_waitcnt vmcnt(0)

; __device__ __forceinline__ unsigned xb_ld(unsigned* p)              { return __hip_atomic_load(p, __ATOMIC_RELAXED, __HIP_MEMORY_SCOPE_AGENT); }
; __device__ __forceinline__ unsigned xb_add(unsigned* p, unsigned v) { return __hip_atomic_fetch_add(p, v, __ATOMIC_RELAXED, __HIP_MEMORY_SCOPE_AGENT); }
; #define XB_SPIN(cond, bar) do { unsigned _sp = 0; while (cond) { __builtin_amdgcn_s_sleep(1); \
;     if ((++_sp & 255u) == 0u) { if (xb_ld(&(bar)[XB_TMO])) break; if (_sp > XB_SPIN_CAP) { atomicAdd(&(bar)[XB_TMO], 1u); break; } } } } while (0)
; __device__ __forceinline__ void xcd_barrier(const XcdBarrier& b) {
;     ...
;             if (og + 1u == (tg + 1u) * nx) xb_add(&bar[XB_TOPGEN], 1u);
;             else XB_SPIN(xb_ld(&bar[XB_TOPGEN]) == tg, bar);
;             __builtin_amdgcn_fence(__ATOMIC_ACQUIRE, "agent");
;             xb_add(&bar[XB_XGEN(b.x)], 1u);
;             asm volatile("s_waitcnt vmcnt(0)" ::: "memory");
.LBB0_848:
	s_or_b64 exec, exec, s[8:9]
	s_mov_b64 s[8:9], exec
	v_mbcnt_lo_u32_b32 v0, s8, 0
	v_mbcnt_hi_u32_b32 v0, s9, v0
	v_cmp_eq_u32_e32 vcc, 0, v0
	s_waitcnt vmcnt(0)
	buffer_inv sc1
	s_and_saveexec_b64 s[10:11], vcc
	s_cbranch_execz .LBB0_850
	s_bcnt1_i32_b64 s2, s[8:9]
	v_mov_b32_e32 v0, s2
	v_readlane_b32 s2, v253, 61
	v_readlane_b32 s3, v253, 62
	s_nop 4
.LBB0_850:
	s_or_b64 exec, exec, s[10:11]
	s_waitcnt vmcnt(0)
